# SSD chunk head: the masked dt loads join the staging batch (one fewer exposed round trip per chunk)
# speedup vs baseline: 1.0086x; 1.0012x over previous
; DI void ssd_item(const Params& p, int l, int it, char* smem) {
;     ...
;     asm volatile("s_waitcnt vmcnt(0)" ::: "memory");
;     bf16x8 creg[8];
;     const u16* cr = XBCA + (rbase + pos0 + w * 32 + l32) * 1024 + 768 + g * 128 + h * 8;
; #pragma unroll
;     for (int ks = 0; ks < 4; ++ks) creg[ks] = *(const bf16x8*)(cr + ks * 16);
;     __builtin_amdgcn_sched_barrier(0);
; #pragma unroll
;     for (int i = 0; i < 8; ++i) {
;       const int q = tid + 256 * i, j = q >> 4, ch = q & 15;
;       *(uint4*)&BG[j * 136 + ch * 8] = *(const uint4*)&XBCA[(rbase + pos0 + j) * 1024 + 512 + g * 128 + ch * 8];
;     }
;     if (w == 0) {
;       const float r0 = DT[(rbase + pos0 + 2 * lane) * 16 + dir * 8 + hd] + dtb;
;       const float r1 = DT[(rbase + pos0 + 2 * lane + 1) * 16 + dir * 8 + hd] + dtb;
.LBB0_989:
	s_add_u32 s78, s81, s86
	s_addc_u32 s79, s80, 0
	v_lshl_add_u64 v[32:33], v[158:159], 0, s[78:79]
	v_lshlrev_b64 v[32:33], 11, v[32:33]
	s_waitcnt vmcnt(0)
	v_lshl_add_u64 v[36:37], v[200:201], 0, v[32:33]
	global_load_dwordx4 v[32:35], v[36:37], off offset:1536
	global_load_dwordx4 v[136:139], v[36:37], off offset:1568
	global_load_dwordx4 v[132:135], v[36:37], off offset:1600
	global_load_dwordx4 v[128:131], v[36:37], off offset:1632
	v_lshl_add_u64 v[42:43], s[78:79], 0, v[162:163]
	v_lshlrev_b64 v[42:43], 11, v[42:43]
	v_lshl_add_u64 v[42:43], v[160:161], 0, v[42:43]
	global_load_dwordx4 v[64:67], v[42:43], off offset:1024
	v_lshl_add_u64 v[44:45], s[78:79], 0, v[166:167]
	v_lshlrev_b64 v[44:45], 11, v[44:45]
	v_lshl_add_u64 v[44:45], v[160:161], 0, v[44:45]
	global_load_dwordx4 v[68:71], v[44:45], off offset:1024
	v_lshl_add_u64 v[46:47], s[78:79], 0, v[170:171]
	v_lshlrev_b64 v[46:47], 11, v[46:47]
	v_lshl_add_u64 v[46:47], v[160:161], 0, v[46:47]
	global_load_dwordx4 v[72:75], v[46:47], off offset:1024
	v_lshl_add_u64 v[48:49], s[78:79], 0, v[178:179]
	v_lshlrev_b64 v[48:49], 11, v[48:49]
	v_lshl_add_u64 v[48:49], v[160:161], 0, v[48:49]
	global_load_dwordx4 v[76:79], v[48:49], off offset:1024
	v_lshl_add_u64 v[50:51], s[78:79], 0, v[182:183]
	v_lshlrev_b64 v[50:51], 11, v[50:51]
	v_lshl_add_u64 v[50:51], v[160:161], 0, v[50:51]
	global_load_dwordx4 v[80:83], v[50:51], off offset:1024
	v_lshl_add_u64 v[52:53], s[78:79], 0, v[186:187]
	v_lshlrev_b64 v[52:53], 11, v[52:53]
	v_lshl_add_u64 v[52:53], v[160:161], 0, v[52:53]
	global_load_dwordx4 v[84:87], v[52:53], off offset:1024
	v_lshl_add_u64 v[54:55], s[78:79], 0, v[190:191]
	v_lshlrev_b64 v[54:55], 11, v[54:55]
	v_lshl_add_u64 v[54:55], v[160:161], 0, v[54:55]
	global_load_dwordx4 v[88:91], v[54:55], off offset:1024
	v_lshl_add_u64 v[56:57], s[78:79], 0, v[194:195]
	v_lshlrev_b64 v[56:57], 11, v[56:57]
	v_lshl_add_u64 v[56:57], v[160:161], 0, v[56:57]
	global_load_dwordx4 v[92:95], v[56:57], off offset:1024
	s_and_saveexec_b64 s[0:1], s[38:39]
	v_lshl_add_u64 v[58:59], s[78:79], 0, v[172:173]
	v_lshlrev_b64 v[58:59], 6, v[58:59]
	v_lshl_add_u64 v[58:59], s[72:73], 0, v[58:59]
	global_load_dword v60, v[58:59], off
	global_load_dword v61, v[58:59], off offset:64
	s_or_b64 exec, exec, s[0:1]
	s_waitcnt vmcnt(0)
	ds_write_b128 v164, v[64:67]
	ds_write_b128 v168, v[68:71]
	ds_write_b128 v176, v[72:75]
	ds_write_b128 v180, v[76:79]
	ds_write_b128 v184, v[80:83]
	ds_write_b128 v188, v[84:87]
	ds_write_b128 v192, v[88:91]
	ds_write_b128 v196, v[92:95]
	s_and_saveexec_b64 s[0:1], s[38:39]
	s_cbranch_execz .LBB0_996
	v_mov_b32_e32 v40, v60
	v_mov_b32_e32 v38, v61
	v_add_f32_e32 v156, v234, v40
	v_cmp_nlt_f32_e32 vcc, s53, v156
	s_and_saveexec_b64 s[34:35], vcc
	s_cbranch_execz .LBB0_992
; DI void ssd_item(const Params& p, int l, int it, char* smem) {
;     ...
;       const float r0 = DT[(rbase + pos0 + 2 * lane) * 16 + dir * 8 + hd] + dtb;
;       const float r1 = DT[(rbase + pos0 + 2 * lane + 1) * 16 + dir * 8 + hd] + dtb;
;       const float dt0 = (r0 > 20.f) ? r0 : log1pf(expf(r0));
;       const float dt1 = (r1 > 20.f) ? r1 : log1pf(expf(r1));
;       const float a0 = dt0 * a, a1 = dt1 * a;
	v_mul_f32_e32 v39, 0x3fb8aa3b, v156
	v_rndne_f32_e32 v40, v39
	v_sub_f32_e32 v41, v39, v40
	v_fma_f32 v39, v156, s2, -v39
	v_fmac_f32_e32 v39, 0x32a5705f, v156
	v_add_f32_e32 v39, v41, v39
	v_cvt_i32_f32_e32 v40, v40
	v_exp_f32_e32 v39, v39
	v_cmp_ngt_f32_e32 vcc, s3, v156
	v_ldexp_f32 v39, v39, v40
	s_nop 0
	v_cndmask_b32_e32 v39, 0, v39, vcc
	v_cmp_nlt_f32_e32 vcc, s58, v156
	s_nop 1
	v_cndmask_b32_e32 v39, v217, v39, vcc
	v_add_f32_e32 v42, 1.0, v39
	v_add_f32_e32 v40, -1.0, v42
	v_sub_f32_e32 v41, v40, v42
	v_add_f32_e32 v41, 1.0, v41
	v_sub_f32_e32 v40, v39, v40
	v_add_f32_e32 v43, v40, v41
	v_frexp_mant_f32_e32 v44, v42
	v_cvt_f64_f32_e32 v[40:41], v42
	v_frexp_exp_i32_f64_e32 v40, v[40:41]
	v_cmp_gt_f32_e32 vcc, s14, v44
	s_nop 1
	v_subbrev_co_u32_e32 v48, vcc, 0, v40, vcc
	v_sub_u32_e32 v40, 0, v48
	v_ldexp_f32 v41, v42, v40
	v_add_f32_e32 v42, -1.0, v41
	v_add_f32_e32 v44, 1.0, v41
	v_ldexp_f32 v40, v43, v40
	v_add_f32_e32 v43, 1.0, v42
	v_add_f32_e32 v45, -1.0, v44
	v_sub_f32_e32 v43, v41, v43
	v_sub_f32_e32 v41, v41, v45
	v_add_f32_e32 v43, v40, v43
	v_add_f32_e32 v40, v40, v41
	v_add_f32_e32 v49, v44, v40
	v_rcp_f32_e32 v51, v49
	v_sub_f32_e32 v41, v44, v49
	v_add_f32_e32 v50, v40, v41
	v_add_f32_e32 v41, v42, v43
	v_mul_f32_e32 v53, v41, v51
	v_sub_f32_e32 v40, v42, v41
	v_mul_f32_e32 v42, v49, v53
	v_fma_f32 v44, v53, v49, -v42
	v_fmac_f32_e32 v44, v53, v50
	v_add_f32_e32 v52, v43, v40
	v_add_f32_e32 v40, v42, v44
	v_sub_f32_e32 v43, v41, v40
	v_pk_add_f32 v[46:47], v[40:41], v[42:43] neg_lo:[0,1] neg_hi:[0,1]
	v_mov_b32_e32 v45, v40
	v_pk_add_f32 v[40:41], v[46:47], v[44:45] neg_lo:[0,1] neg_hi:[0,1]
	v_cmp_neq_f32_e32 vcc, s59, v39
	v_add_f32_e32 v41, v52, v41
	v_add_f32_e32 v40, v40, v41
	v_add_f32_e32 v41, v43, v40
	v_mul_f32_e32 v52, v51, v41
	v_mul_f32_e32 v42, v49, v52
	v_fma_f32 v44, v52, v49, -v42
	v_fmac_f32_e32 v44, v52, v50
	v_sub_f32_e32 v43, v43, v41
	v_add_f32_e32 v49, v40, v43
	v_add_f32_e32 v40, v42, v44
	v_sub_f32_e32 v43, v41, v40
	v_pk_add_f32 v[46:47], v[40:41], v[42:43] neg_lo:[0,1] neg_hi:[0,1]
	v_mov_b32_e32 v45, v40
	v_pk_add_f32 v[40:41], v[46:47], v[44:45] neg_lo:[0,1] neg_hi:[0,1]
	s_nop 0
	v_add_f32_e32 v41, v49, v41
	v_add_f32_e32 v40, v40, v41
	v_add_f32_e32 v41, v53, v52
	v_add_f32_e32 v40, v43, v40
	v_sub_f32_e32 v42, v41, v53
	v_mul_f32_e32 v40, v51, v40
	v_sub_f32_e32 v42, v52, v42
	v_add_f32_e32 v42, v42, v40
	v_add_f32_e32 v44, v41, v42
	v_mul_f32_e32 v45, v44, v44
	v_fmamk_f32 v40, v45, 0x3e9b6dac, v205
	v_fmaak_f32 v175, v45, v40, 0x3f2aaada
	v_cvt_f32_i32_e32 v40, v48
	v_sub_f32_e32 v41, v44, v41
	v_sub_f32_e32 v41, v42, v41
	v_ldexp_f32 v46, v41, 1
	v_mul_f32_e32 v41, v44, v45
	v_ldexp_f32 v43, v44, 1
	v_pk_mul_f32 v[44:45], v[40:41], v[174:175]
	s_nop 0
	v_fma_f32 v42, v40, s15, -v44
	v_fmac_f32_e32 v42, 0xb102e308, v40
	v_pk_add_f32 v[40:41], v[44:45], v[42:43]
	s_nop 0
	v_sub_f32_e32 v43, v41, v43
	v_sub_f32_e32 v43, v45, v43
	v_add_f32_e32 v47, v46, v43
	v_mov_b32_e32 v46, v44
	v_pk_add_f32 v[44:45], v[40:41], v[44:45] neg_lo:[0,1] neg_hi:[0,1]
	v_pk_add_f32 v[48:49], v[40:41], v[46:47]
	v_mov_b32_e32 v43, v40
	v_mov_b32_e32 v45, v49
	v_pk_add_f32 v[50:51], v[42:43], v[44:45] neg_lo:[0,1] neg_hi:[0,1]
	v_pk_add_f32 v[42:43], v[42:43], v[44:45]
	v_mov_b32_e32 v46, v47
	v_pk_add_f32 v[44:45], v[42:43], v[40:41] op_sel:[1,0] op_sel_hi:[0,1] neg_lo:[0,1] neg_hi:[0,1]
	v_pk_add_f32 v[52:53], v[48:49], v[44:45] op_sel_hi:[1,0] neg_lo:[0,1] neg_hi:[0,1]
	v_mov_b32_e32 v48, v49
	v_mov_b32_e32 v49, v43
	v_pk_mov_b32 v[44:45], v[40:41], v[44:45] op_sel:[1,0]
	v_mov_b32_e32 v47, v40
	v_pk_add_f32 v[44:45], v[48:49], v[44:45] neg_lo:[0,1] neg_hi:[0,1]
	v_mov_b32_e32 v52, v50
	v_pk_add_f32 v[40:41], v[46:47], v[44:45] neg_lo:[0,1] neg_hi:[0,1]
	v_mov_b32_e32 v51, v43
	v_pk_add_f32 v[44:45], v[52:53], v[40:41]
	s_nop 0
	v_pk_add_f32 v[46:47], v[44:45], v[44:45] op_sel:[0,1] op_sel_hi:[1,0]
	s_nop 0
	v_pk_add_f32 v[42:43], v[42:43], v[46:47] op_sel:[1,0] op_sel_hi:[0,1]
	v_mov_b32_e32 v45, v42
	v_pk_add_f32 v[48:49], v[44:45], v[50:51] neg_lo:[0,1] neg_hi:[0,1]
	v_mov_b32_e32 v41, v46
	v_sub_f32_e32 v43, v44, v48
	v_pk_add_f32 v[40:41], v[40:41], v[48:49] neg_lo:[0,1] neg_hi:[0,1]
	v_sub_f32_e32 v43, v50, v43
	v_add_f32_e32 v40, v40, v43
	v_add_f32_e32 v40, v40, v41
	v_add_f32_e32 v40, v42, v40
	v_cndmask_b32_e32 v40, v217, v40, vcc
	v_cmp_lt_f32_e64 vcc, |v39|, s12
	s_nop 1
	v_cndmask_b32_e32 v156, v40, v39, vcc
